# P7 small-tile GEMM K-loop rewritten: double-buffered A/B LDS images at a conflict-free 544-byte pitch, two-step-ahead register staging, one barrier per 256-deep step
# speedup vs baseline: 1.0126x; 1.0126x over previous
; #define LBAR() asm volatile("s_waitcnt lgkmcnt(0)\n\ts_barrier" ::: "memory")
; #define SG_LOAD(k0) do { _Pragma("unroll") for (int i_ = 0; i_ < 4; ++i_) { const int id_ = tid + i_ * 512, rr_ = id_ >> 5, cc_ = id_ & 31; \
;         ra[i_] = *(const u32x4*)(Ag + (size_t)rr_ * lda + (k0) + cc_ * 8); rb[i_] = *(const u32x4*)(Bg + (size_t)rr_ * ldb + (k0) + cc_ * 8); } } while (0)
; template <class Epi>
; __device__ __forceinline__ void small_gemm_tile(unsigned char* lds, const bf16_t* A, int lda, const bf16_t* Bt, int ldb, int K, int kbreak, int rowbase, int tm, int tn, const Epi& E, int tid) {
;     const int lane = tid & 63, wave = tid >> 6, r16 = lane & 15, q4 = lane >> 4, wm = wave >> 1, wn = wave & 1;
;     unsigned char* AS = lds; unsigned char* BS = lds + 33792; float* RED = (float*)(lds + 67584);
;     const bf16_t* Ag = A + (size_t)(rowbase + tm * 64) * lda; const bf16_t* Bg = Bt + (size_t)(tn * 64) * ldb;
;     u32x4 ra[4], rb[4];
;     ...
;     f32x4 cur[2], first[2];
; #pragma unroll
;     for (int n_ = 0; n_ < 2; ++n_) { cur[n_] = (f32x4){0.f, 0.f, 0.f, 0.f}; first[n_] = (f32x4){0.f, 0.f, 0.f, 0.f}; }
;     SG_LOAD(0);
;     for (int k0 = 0; k0 < K; k0 += 256) {
; #pragma unroll
;         for (int i = 0; i < 4; ++i) { const int id = tid + i * 512, rr = id >> 5, cc = id & 31; *(u32x4*)(AS + rr * 528 + cc * 16) = ra[i]; *(u32x4*)(BS + rr * 528 + cc * 16) = rb[i]; }
;         LBAR();
;         if (k0 + 256 < K) SG_LOAD(k0 + 256);
.LBB0_1000:
	s_and_b32 s16, s25, 31
	s_lshl_b32 s16, s16, 20
	s_lshl_b32 s16, s26, 1
	s_andn2_b32 s16, s16, 63
	s_add_i32 s20, s16, 0x4000
	s_and_b32 s27, s26, 31
	s_ashr_i32 s21, s20, 31
	s_lshl_b64 s[22:23], s[20:21], 14
	s_lshl_b32 s16, s27, 20
	v_mov_b32_e32 v36, 0
	v_mov_b32_e32 v37, 0
	v_mov_b32_e32 v38, 0
	v_mov_b32_e32 v39, 0
	v_mov_b32_e32 v16, 0
	v_mov_b32_e32 v17, 0
	v_mov_b32_e32 v18, 0
	v_mov_b32_e32 v19, 0
	v_and_b32_e32 v64, 15, v188
	v_bfe_u32 v65, v188, 4, 2
	v_lshrrev_b32_e32 v66, 7, v188
	v_bfe_u32 v67, v188, 6, 1
	v_lshrrev_b32_e32 v68, 5, v188
	v_and_b32_e32 v69, 31, v188
	v_lshlrev_b32_e32 v70, 14, v68
	v_lshl_add_u32 v70, v69, 4, v70
	v_mov_b32_e32 v71, 0
	s_add_u32 s30, s74, s22
	s_addc_u32 s31, s75, s23
	s_mov_b64 s[34:35], 0x40000
	v_lshl_add_u64 v[42:43], s[30:31], 0, v[70:71]
	v_lshl_add_u64 v[44:45], v[42:43], 0, s[34:35]
	v_lshl_add_u64 v[46:47], v[44:45], 0, s[34:35]
	v_lshl_add_u64 v[48:49], v[46:47], 0, s[34:35]
	s_add_u32 s30, s86, 0x6400000
	s_addc_u32 s31, s87, 0
	s_add_u32 s30, s30, s16
	s_addc_u32 s31, s31, 0
	v_lshl_add_u64 v[50:51], s[30:31], 0, v[70:71]
	v_lshl_add_u64 v[52:53], v[50:51], 0, s[34:35]
	v_lshl_add_u64 v[54:55], v[52:53], 0, s[34:35]
	v_lshl_add_u64 v[56:57], v[54:55], 0, s[34:35]
	v_mul_u32_u24_e32 v58, 0x220, v68
	v_lshl_add_u32 v58, v69, 4, v58
	v_add_u32_e32 v59, 0x11000, v58
	v_lshl_add_u32 v60, v66, 4, v64
	v_mul_u32_u24_e32 v60, 0x220, v60
	v_lshl_add_u32 v60, v65, 4, v60
	v_add_u32_e32 v61, 0x11000, v60
	v_lshl_add_u32 v62, v67, 5, v64
	v_mul_u32_u24_e32 v62, 0x220, v62
	v_lshl_add_u32 v62, v65, 4, v62
	v_add_u32_e32 v62, 0x8800, v62
	v_add_u32_e32 v63, 0x11000, v62
	s_mov_b32 s29, 16
	global_load_dwordx4 v[0:3], v[42:43], off
	global_load_dwordx4 v[4:7], v[44:45], off
	global_load_dwordx4 v[8:11], v[46:47], off
	global_load_dwordx4 v[12:15], v[48:49], off
	global_load_dwordx4 v[20:23], v[50:51], off
	global_load_dwordx4 v[24:27], v[52:53], off
	global_load_dwordx4 v[28:31], v[54:55], off
	global_load_dwordx4 v[32:35], v[56:57], off
	v_lshl_add_u64 v[42:43], v[42:43], 0, s[18:19]
	v_lshl_add_u64 v[44:45], v[44:45], 0, s[18:19]
	v_lshl_add_u64 v[46:47], v[46:47], 0, s[18:19]
	v_lshl_add_u64 v[48:49], v[48:49], 0, s[18:19]
	v_lshl_add_u64 v[50:51], v[50:51], 0, s[18:19]
	v_lshl_add_u64 v[52:53], v[52:53], 0, s[18:19]
	v_lshl_add_u64 v[54:55], v[54:55], 0, s[18:19]
	v_lshl_add_u64 v[56:57], v[56:57], 0, s[18:19]
	global_load_dwordx4 v[110:113], v[42:43], off
	global_load_dwordx4 v[114:117], v[44:45], off
	global_load_dwordx4 v[118:121], v[46:47], off
	global_load_dwordx4 v[122:125], v[48:49], off
	global_load_dwordx4 v[126:129], v[50:51], off
	global_load_dwordx4 v[130:133], v[52:53], off
	global_load_dwordx4 v[134:137], v[54:55], off
	global_load_dwordx4 v[138:141], v[56:57], off
	v_lshl_add_u64 v[42:43], v[42:43], 0, s[18:19]
	v_lshl_add_u64 v[44:45], v[44:45], 0, s[18:19]
	v_lshl_add_u64 v[46:47], v[46:47], 0, s[18:19]
	v_lshl_add_u64 v[48:49], v[48:49], 0, s[18:19]
	v_lshl_add_u64 v[50:51], v[50:51], 0, s[18:19]
	v_lshl_add_u64 v[52:53], v[52:53], 0, s[18:19]
	v_lshl_add_u64 v[54:55], v[54:55], 0, s[18:19]
	v_lshl_add_u64 v[56:57], v[56:57], 0, s[18:19]
	s_waitcnt vmcnt(8)
	ds_write_b128 v58, v[0:3]
	ds_write_b128 v58, v[4:7] offset:8704
	ds_write_b128 v58, v[8:11] offset:17408
	ds_write_b128 v58, v[12:15] offset:26112
	ds_write_b128 v58, v[20:23] offset:34816
	ds_write_b128 v58, v[24:27] offset:43520
	ds_write_b128 v58, v[28:31] offset:52224
	ds_write_b128 v58, v[32:35] offset:60928
	global_load_dwordx4 v[0:3], v[42:43], off
	global_load_dwordx4 v[4:7], v[44:45], off
	global_load_dwordx4 v[8:11], v[46:47], off
	global_load_dwordx4 v[12:15], v[48:49], off
	global_load_dwordx4 v[20:23], v[50:51], off
	global_load_dwordx4 v[24:27], v[52:53], off
	global_load_dwordx4 v[28:31], v[54:55], off
	global_load_dwordx4 v[32:35], v[56:57], off
	v_lshl_add_u64 v[42:43], v[42:43], 0, s[18:19]
	v_lshl_add_u64 v[44:45], v[44:45], 0, s[18:19]
	v_lshl_add_u64 v[46:47], v[46:47], 0, s[18:19]
	v_lshl_add_u64 v[48:49], v[48:49], 0, s[18:19]
	v_lshl_add_u64 v[50:51], v[50:51], 0, s[18:19]
	v_lshl_add_u64 v[52:53], v[52:53], 0, s[18:19]
	v_lshl_add_u64 v[54:55], v[54:55], 0, s[18:19]
	v_lshl_add_u64 v[56:57], v[56:57], 0, s[18:19]
	s_waitcnt lgkmcnt(0)
	s_barrier
; #define LBAR() asm volatile("s_waitcnt lgkmcnt(0)\n\ts_barrier" ::: "memory")
; #define SG_LOAD(k0) do { _Pragma("unroll") for (int i_ = 0; i_ < 4; ++i_) { const int id_ = tid + i_ * 512, rr_ = id_ >> 5, cc_ = id_ & 31; \
;         ra[i_] = *(const u32x4*)(Ag + (size_t)rr_ * lda + (k0) + cc_ * 8); rb[i_] = *(const u32x4*)(Bg + (size_t)rr_ * ldb + (k0) + cc_ * 8); } } while (0)
; template <class Epi>
; __device__ __forceinline__ void small_gemm_tile(unsigned char* lds, const bf16_t* A, int lda, const bf16_t* Bt, int ldb, int K, int kbreak, int rowbase, int tm, int tn, const Epi& E, int tid) {
;     ...
;     for (int k0 = 0; k0 < K; k0 += 256) {
; #pragma unroll
;         for (int i = 0; i < 4; ++i) { const int id = tid + i * 512, rr = id >> 5, cc = id & 31; *(u32x4*)(AS + rr * 528 + cc * 16) = ra[i]; *(u32x4*)(BS + rr * 528 + cc * 16) = rb[i]; }
;         LBAR();
;         if (k0 + 256 < K) SG_LOAD(k0 + 256);
;         if (k0 == kbreak) {
; #pragma unroll
;             for (int n_ = 0; n_ < 2; ++n_) { first[n_] = cur[n_]; cur[n_] = (f32x4){0.f, 0.f, 0.f, 0.f}; } }
; #pragma unroll
;         for (int kk = 0; kk < 8; ++kk) { const bf16x8 af = *(const bf16x8*)(AS + (wm * 16 + r16) * 528 + kk * 64 + q4 * 16);
; #pragma unroll
;             for (int nt = 0; nt < 2; ++nt) { const bf16x8 bfg = *(const bf16x8*)(BS + (wn * 32 + nt * 16 + r16) * 528 + kk * 64 + q4 * 16); cur[nt] = __builtin_amdgcn_mfma_f32_16x16x32_bf16(bfg, af, cur[nt], 0, 0, 0); } }
;         LBAR();
;     }
.Lp7n_loop:
	s_waitcnt vmcnt(8)
	ds_write_b128 v59, v[110:113]
	ds_write_b128 v59, v[114:117] offset:8704
	ds_write_b128 v59, v[118:121] offset:17408
	ds_write_b128 v59, v[122:125] offset:26112
	ds_write_b128 v59, v[126:129] offset:34816
	ds_write_b128 v59, v[130:133] offset:43520
	ds_write_b128 v59, v[134:137] offset:52224
	ds_write_b128 v59, v[138:141] offset:60928
	global_load_dwordx4 v[110:113], v[42:43], off
	global_load_dwordx4 v[114:117], v[44:45], off
	global_load_dwordx4 v[118:121], v[46:47], off
	global_load_dwordx4 v[122:125], v[48:49], off
	global_load_dwordx4 v[126:129], v[50:51], off
	global_load_dwordx4 v[130:133], v[52:53], off
	global_load_dwordx4 v[134:137], v[54:55], off
	global_load_dwordx4 v[138:141], v[56:57], off
	v_lshl_add_u64 v[42:43], v[42:43], 0, s[18:19]
	v_lshl_add_u64 v[44:45], v[44:45], 0, s[18:19]
	v_lshl_add_u64 v[46:47], v[46:47], 0, s[18:19]
	v_lshl_add_u64 v[48:49], v[48:49], 0, s[18:19]
	v_lshl_add_u64 v[50:51], v[50:51], 0, s[18:19]
	v_lshl_add_u64 v[52:53], v[52:53], 0, s[18:19]
	v_lshl_add_u64 v[54:55], v[54:55], 0, s[18:19]
	v_lshl_add_u64 v[56:57], v[56:57], 0, s[18:19]
	ds_read_b128 v[90:93], v60
	ds_read_b128 v[94:97], v62
	ds_read_b128 v[98:101], v62 offset:8704
	ds_read_b128 v[102:105], v60 offset:64
	ds_read_b128 v[106:109], v62 offset:64
	ds_read_b128 v[190:193], v62 offset:8768
	s_waitcnt lgkmcnt(3)
	v_mfma_f32_16x16x32_bf16 v[36:39], v[94:97], v[90:93], v[36:39]
	v_mfma_f32_16x16x32_bf16 v[16:19], v[98:101], v[90:93], v[16:19]
	ds_read_b128 v[194:197], v60 offset:128
	ds_read_b128 v[198:201], v62 offset:128
	ds_read_b128 v[202:205], v62 offset:8832
	ds_read_b128 v[206:209], v60 offset:192
	ds_read_b128 v[210:213], v62 offset:192
	ds_read_b128 v[214:217], v62 offset:8896
	ds_read_b128 v[90:93], v60 offset:256
	ds_read_b128 v[94:97], v62 offset:256
	ds_read_b128 v[98:101], v62 offset:8960
	s_waitcnt lgkmcnt(9)
	v_mfma_f32_16x16x32_bf16 v[36:39], v[106:109], v[102:105], v[36:39]
	v_mfma_f32_16x16x32_bf16 v[16:19], v[190:193], v[102:105], v[16:19]
	ds_read_b128 v[102:105], v60 offset:320
	ds_read_b128 v[106:109], v62 offset:320
	ds_read_b128 v[190:193], v62 offset:9024
	s_waitcnt lgkmcnt(9)
	v_mfma_f32_16x16x32_bf16 v[36:39], v[198:201], v[194:197], v[36:39]
	v_mfma_f32_16x16x32_bf16 v[16:19], v[202:205], v[194:197], v[16:19]
	ds_read_b128 v[194:197], v60 offset:384
	ds_read_b128 v[198:201], v62 offset:384
	ds_read_b128 v[202:205], v62 offset:9088
	s_waitcnt lgkmcnt(9)
	v_mfma_f32_16x16x32_bf16 v[36:39], v[210:213], v[206:209], v[36:39]
	v_mfma_f32_16x16x32_bf16 v[16:19], v[214:217], v[206:209], v[16:19]
	ds_read_b128 v[206:209], v60 offset:448
	ds_read_b128 v[210:213], v62 offset:448
	ds_read_b128 v[214:217], v62 offset:9152
	s_waitcnt lgkmcnt(9)
	v_mfma_f32_16x16x32_bf16 v[36:39], v[94:97], v[90:93], v[36:39]
	v_mfma_f32_16x16x32_bf16 v[16:19], v[98:101], v[90:93], v[16:19]
	s_waitcnt lgkmcnt(6)
	v_mfma_f32_16x16x32_bf16 v[36:39], v[106:109], v[102:105], v[36:39]
	v_mfma_f32_16x16x32_bf16 v[16:19], v[190:193], v[102:105], v[16:19]
	s_waitcnt lgkmcnt(3)
	v_mfma_f32_16x16x32_bf16 v[36:39], v[198:201], v[194:197], v[36:39]
	v_mfma_f32_16x16x32_bf16 v[16:19], v[202:205], v[194:197], v[16:19]
	s_waitcnt lgkmcnt(0)
	v_mfma_f32_16x16x32_bf16 v[36:39], v[210:213], v[206:209], v[36:39]
	v_mfma_f32_16x16x32_bf16 v[16:19], v[214:217], v[206:209], v[16:19]
	s_waitcnt lgkmcnt(0)
	s_barrier
	s_waitcnt vmcnt(8)
	ds_write_b128 v58, v[0:3]
	ds_write_b128 v58, v[4:7] offset:8704
	ds_write_b128 v58, v[8:11] offset:17408
	ds_write_b128 v58, v[12:15] offset:26112
	ds_write_b128 v58, v[20:23] offset:34816
	ds_write_b128 v58, v[24:27] offset:43520
	ds_write_b128 v58, v[28:31] offset:52224
	ds_write_b128 v58, v[32:35] offset:60928
	global_load_dwordx4 v[0:3], v[42:43], off
	global_load_dwordx4 v[4:7], v[44:45], off
	global_load_dwordx4 v[8:11], v[46:47], off
	global_load_dwordx4 v[12:15], v[48:49], off
	global_load_dwordx4 v[20:23], v[50:51], off
	global_load_dwordx4 v[24:27], v[52:53], off
	global_load_dwordx4 v[28:31], v[54:55], off
	global_load_dwordx4 v[32:35], v[56:57], off
	v_lshl_add_u64 v[42:43], v[42:43], 0, s[18:19]
	v_lshl_add_u64 v[44:45], v[44:45], 0, s[18:19]
	v_lshl_add_u64 v[46:47], v[46:47], 0, s[18:19]
	v_lshl_add_u64 v[48:49], v[48:49], 0, s[18:19]
	v_lshl_add_u64 v[50:51], v[50:51], 0, s[18:19]
	v_lshl_add_u64 v[52:53], v[52:53], 0, s[18:19]
	v_lshl_add_u64 v[54:55], v[54:55], 0, s[18:19]
	v_lshl_add_u64 v[56:57], v[56:57], 0, s[18:19]
	ds_read_b128 v[90:93], v61
	ds_read_b128 v[94:97], v63
	ds_read_b128 v[98:101], v63 offset:8704
	ds_read_b128 v[102:105], v61 offset:64
	ds_read_b128 v[106:109], v63 offset:64
	ds_read_b128 v[190:193], v63 offset:8768
	s_waitcnt lgkmcnt(3)
	v_mfma_f32_16x16x32_bf16 v[36:39], v[94:97], v[90:93], v[36:39]
	v_mfma_f32_16x16x32_bf16 v[16:19], v[98:101], v[90:93], v[16:19]
	ds_read_b128 v[194:197], v61 offset:128
	ds_read_b128 v[198:201], v63 offset:128
	ds_read_b128 v[202:205], v63 offset:8832
	ds_read_b128 v[206:209], v61 offset:192
	ds_read_b128 v[210:213], v63 offset:192
	ds_read_b128 v[214:217], v63 offset:8896
	ds_read_b128 v[90:93], v61 offset:256
	ds_read_b128 v[94:97], v63 offset:256
	ds_read_b128 v[98:101], v63 offset:8960
	s_waitcnt lgkmcnt(9)
	v_mfma_f32_16x16x32_bf16 v[36:39], v[106:109], v[102:105], v[36:39]
	v_mfma_f32_16x16x32_bf16 v[16:19], v[190:193], v[102:105], v[16:19]
	ds_read_b128 v[102:105], v61 offset:320
	ds_read_b128 v[106:109], v63 offset:320
	ds_read_b128 v[190:193], v63 offset:9024
	s_waitcnt lgkmcnt(9)
	v_mfma_f32_16x16x32_bf16 v[36:39], v[198:201], v[194:197], v[36:39]
	v_mfma_f32_16x16x32_bf16 v[16:19], v[202:205], v[194:197], v[16:19]
	ds_read_b128 v[194:197], v61 offset:384
	ds_read_b128 v[198:201], v63 offset:384
	ds_read_b128 v[202:205], v63 offset:9088
	s_waitcnt lgkmcnt(9)
	v_mfma_f32_16x16x32_bf16 v[36:39], v[210:213], v[206:209], v[36:39]
	v_mfma_f32_16x16x32_bf16 v[16:19], v[214:217], v[206:209], v[16:19]
	ds_read_b128 v[206:209], v61 offset:448
	ds_read_b128 v[210:213], v63 offset:448
	ds_read_b128 v[214:217], v63 offset:9152
	s_waitcnt lgkmcnt(9)
	v_mfma_f32_16x16x32_bf16 v[36:39], v[94:97], v[90:93], v[36:39]
	v_mfma_f32_16x16x32_bf16 v[16:19], v[98:101], v[90:93], v[16:19]
	s_waitcnt lgkmcnt(6)
	v_mfma_f32_16x16x32_bf16 v[36:39], v[106:109], v[102:105], v[36:39]
	v_mfma_f32_16x16x32_bf16 v[16:19], v[190:193], v[102:105], v[16:19]
	s_waitcnt lgkmcnt(3)
	v_mfma_f32_16x16x32_bf16 v[36:39], v[198:201], v[194:197], v[36:39]
	v_mfma_f32_16x16x32_bf16 v[16:19], v[202:205], v[194:197], v[16:19]
	s_waitcnt lgkmcnt(0)
	v_mfma_f32_16x16x32_bf16 v[36:39], v[210:213], v[206:209], v[36:39]
	v_mfma_f32_16x16x32_bf16 v[16:19], v[214:217], v[206:209], v[16:19]
	s_waitcnt lgkmcnt(0)
	s_barrier
	s_add_i32 s29, s29, -1
	s_cmp_lg_u32 s29, 0
	s_cbranch_scc1 .Lp7n_loop
	s_waitcnt vmcnt(0)
